# norm phases: y/y2 partial loads issued together with the H loads instead of 16 serialized load+wait steps
# speedup vs baseline: 1.0290x; 1.0290x over previous
; __device__ __forceinline__ void norm_phase(const Ctx& cx, const Params& p, NormArgs a) {
;     ...
;     if (a.first) {
;       const float* src = t < 256 ? p.ctx + ((size_t)b * 256 + t) * DM : p.x + ((size_t)b * 2048 + (t - 256)) * DM;
; #pragma unroll
;       for (int i = 0; i < 8; ++i) h[i] = *reinterpret_cast<const float4*>(src + i * 256 + lane * 4);
;     } else {
; #pragma unroll
;       for (int i = 0; i < 8; ++i) {
;         uint2 hb = *reinterpret_cast<const uint2*>(H + (size_t)row * DM + i * 256 + lane * 4);
;         h[i].x = __uint_as_float(hb.x << 16); h[i].y = __uint_as_float(hb.x & 0xffff0000u);
;         h[i].z = __uint_as_float(hb.y << 16); h[i].w = __uint_as_float(hb.y & 0xffff0000u);
;       }
;     }
;     if (a.y) {
;       float4 y[8];
;       float ss = 0.f;
; #pragma unroll
;       for (int i = 0; i < 8; ++i) {
;         {
;           uint2 yb = *reinterpret_cast<const uint2*>(a.y + (size_t)row * DM + i * 256 + lane * 4);
;           y[i].x = __uint_as_float(yb.x << 16); y[i].y = __uint_as_float(yb.x & 0xffff0000u);
;           y[i].z = __uint_as_float(yb.y << 16); y[i].w = __uint_as_float(yb.y & 0xffff0000u);
;         }
;         if (a.y2) {
;           uint2 yb = *reinterpret_cast<const uint2*>(a.y2 + (size_t)row * DM + i * 256 + lane * 4);
;           y[i].x += __uint_as_float(yb.x << 16); y[i].y += __uint_as_float(yb.x & 0xffff0000u);
;           y[i].z += __uint_as_float(yb.y << 16); y[i].w += __uint_as_float(yb.y & 0xffff0000u);
;         }
.LBB0_885:
	s_andn2_b64 vcc, exec, s[2:3]
	v_ashrrev_i32_e32 v47, 31, v46
	s_cbranch_vccnz .LBB0_887
	s_waitcnt vmcnt(0)
	v_lshlrev_b64 v[0:1], 12, v[46:47]
	v_lshl_add_u64 v[0:1], v[36:37], 0, v[0:1]
	global_load_dwordx2 v[2:3], v[0:1], off
	global_load_dwordx2 v[4:5], v[0:1], off offset:512
	global_load_dwordx2 v[6:7], v[0:1], off offset:1024
	global_load_dwordx2 v[8:9], v[0:1], off offset:1536
	global_load_dwordx2 v[10:11], v[0:1], off offset:2048
	global_load_dwordx2 v[52:53], v[0:1], off offset:2560
	global_load_dwordx2 v[54:55], v[0:1], off offset:3072
	global_load_dwordx2 v[56:57], v[0:1], off offset:3584
	s_and_b64 vcc, exec, s[40:41]
	s_cbranch_vccnz .Lnorm_pf_done
	v_lshlrev_b64 v[164:165], 12, v[46:47]
	v_lshl_add_u64 v[166:167], v[38:39], 0, v[164:165]
	v_lshl_add_u64 v[168:169], v[40:41], 0, v[164:165]
	global_load_dwordx2 v[120:121], v[166:167], off
	global_load_dwordx2 v[122:123], v[166:167], off offset:512
	global_load_dwordx2 v[124:125], v[166:167], off offset:1024
	global_load_dwordx2 v[126:127], v[166:167], off offset:1536
	global_load_dwordx2 v[128:129], v[166:167], off offset:2048
	global_load_dwordx2 v[130:131], v[166:167], off offset:2560
	global_load_dwordx2 v[132:133], v[166:167], off offset:3072
	global_load_dwordx2 v[134:135], v[166:167], off offset:3584
	s_andn2_b64 vcc, exec, s[16:17]
	s_cbranch_vccnz .Lnorm_pf_done
	global_load_dwordx2 v[136:137], v[168:169], off
	global_load_dwordx2 v[138:139], v[168:169], off offset:512
	global_load_dwordx2 v[140:141], v[168:169], off offset:1024
	global_load_dwordx2 v[142:143], v[168:169], off offset:1536
	global_load_dwordx2 v[144:145], v[168:169], off offset:2048
	global_load_dwordx2 v[146:147], v[168:169], off offset:2560
	global_load_dwordx2 v[148:149], v[168:169], off offset:3072
	global_load_dwordx2 v[150:151], v[168:169], off offset:3584
.Lnorm_pf_done:
	s_waitcnt vmcnt(0)
	v_lshlrev_b32_e32 v32, 16, v2
	v_and_b32_e32 v33, 0xffff0000, v2
	v_lshlrev_b32_e32 v34, 16, v3
	v_and_b32_e32 v35, 0xffff0000, v3
	v_lshlrev_b32_e32 v28, 16, v4
	v_and_b32_e32 v29, 0xffff0000, v4
	v_lshlrev_b32_e32 v30, 16, v5
	v_and_b32_e32 v31, 0xffff0000, v5
	v_lshlrev_b32_e32 v24, 16, v6
	v_and_b32_e32 v25, 0xffff0000, v6
	v_lshlrev_b32_e32 v26, 16, v7
	v_and_b32_e32 v27, 0xffff0000, v7
	v_lshlrev_b32_e32 v20, 16, v8
	v_and_b32_e32 v21, 0xffff0000, v8
	v_lshlrev_b32_e32 v22, 16, v9
	v_and_b32_e32 v23, 0xffff0000, v9
	v_lshlrev_b32_e32 v12, 16, v10
	v_and_b32_e32 v13, 0xffff0000, v10
	v_lshlrev_b32_e32 v14, 16, v11
	v_and_b32_e32 v15, 0xffff0000, v11
	v_lshlrev_b32_e32 v8, 16, v52
	v_and_b32_e32 v9, 0xffff0000, v52
	v_lshlrev_b32_e32 v10, 16, v53
	v_and_b32_e32 v11, 0xffff0000, v53
	v_lshlrev_b32_e32 v4, 16, v54
	v_and_b32_e32 v5, 0xffff0000, v54
	v_lshlrev_b32_e32 v6, 16, v55
	v_and_b32_e32 v7, 0xffff0000, v55
	v_lshlrev_b32_e32 v0, 16, v56
	v_and_b32_e32 v1, 0xffff0000, v56
	v_lshlrev_b32_e32 v2, 16, v57
	v_and_b32_e32 v3, 0xffff0000, v57
; __device__ __forceinline__ void norm_phase(const Ctx& cx, const Params& p, NormArgs a) {
;     ...
;     int v = t < 256 ? 4 : b;
;     const float* PS = PL + 4096 + (v == v0 ? 0 : 6144);
;     float4 h[8];
;     if (a.first) {
;       const float* src = t < 256 ? p.ctx + ((size_t)b * 256 + t) * DM : p.x + ((size_t)b * 2048 + (t - 256)) * DM;
; #pragma unroll
;       for (int i = 0; i < 8; ++i) h[i] = *reinterpret_cast<const float4*>(src + i * 256 + lane * 4);
;     } else {
; #pragma unroll
;       for (int i = 0; i < 8; ++i) {
;         uint2 hb = *reinterpret_cast<const uint2*>(H + (size_t)row * DM + i * 256 + lane * 4);
;         h[i].x = __uint_as_float(hb.x << 16); h[i].y = __uint_as_float(hb.x & 0xffff0000u);
;         h[i].z = __uint_as_float(hb.y << 16); h[i].w = __uint_as_float(hb.y & 0xffff0000u);
;       }
;     }
;     if (a.y) {
;       float4 y[8];
;       float ss = 0.f;
; #pragma unroll
;       for (int i = 0; i < 8; ++i) {
;         {
;           uint2 yb = *reinterpret_cast<const uint2*>(a.y + (size_t)row * DM + i * 256 + lane * 4);
;           y[i].x = __uint_as_float(yb.x << 16); y[i].y = __uint_as_float(yb.x & 0xffff0000u);
;           y[i].z = __uint_as_float(yb.y << 16); y[i].w = __uint_as_float(yb.y & 0xffff0000u);
;         }
;         if (a.y2) {
;           uint2 yb = *reinterpret_cast<const uint2*>(a.y2 + (size_t)row * DM + i * 256 + lane * 4);
;           y[i].x += __uint_as_float(yb.x << 16); y[i].y += __uint_as_float(yb.x & 0xffff0000u);
;           y[i].z += __uint_as_float(yb.y << 16); y[i].w += __uint_as_float(yb.y & 0xffff0000u);
;         }
.LBB0_887:
	v_cndmask_b32_e64 v52, v48, 4, s[0:1]
	v_cmp_eq_u32_e32 vcc, v52, v19
	v_mov_b32_e32 v52, 0x6000
	s_nop 0
	v_cndmask_b32_e64 v52, v52, 0, vcc
	s_and_b64 vcc, exec, s[40:41]
	v_add_u32_e32 v88, v197, v52
	s_cbranch_vccnz .LBB0_905
	v_cndmask_b32_e64 v54, 0, 1, s[16:17]
	s_nop 0
	v_cmp_ne_u32_e64 s[0:1], 1, v54
	s_andn2_b64 vcc, exec, s[16:17]
	s_cbranch_vccnz .Lnorm_noy2
	v_lshlrev_b32_e32 v54, 16, v120
	v_and_b32_e32 v55, 0xffff0000, v120
	v_lshlrev_b32_e32 v52, 16, v121
	v_and_b32_e32 v53, 0xffff0000, v121
	v_lshlrev_b32_e32 v160, 16, v136
	v_and_b32_e32 v161, 0xffff0000, v136
	v_lshlrev_b32_e32 v162, 16, v137
	v_and_b32_e32 v163, 0xffff0000, v137
	v_pk_add_f32 v[54:55], v[54:55], v[160:161]
	v_pk_add_f32 v[52:53], v[52:53], v[162:163]
	v_lshlrev_b32_e32 v60, 16, v122
	v_and_b32_e32 v61, 0xffff0000, v122
	v_lshlrev_b32_e32 v58, 16, v123
	v_and_b32_e32 v59, 0xffff0000, v123
	v_lshlrev_b32_e32 v160, 16, v138
	v_and_b32_e32 v161, 0xffff0000, v138
	v_lshlrev_b32_e32 v162, 16, v139
	v_and_b32_e32 v163, 0xffff0000, v139
	v_pk_add_f32 v[60:61], v[60:61], v[160:161]
	v_pk_add_f32 v[58:59], v[58:59], v[162:163]
	v_lshlrev_b32_e32 v64, 16, v124
	v_and_b32_e32 v65, 0xffff0000, v124
	v_lshlrev_b32_e32 v62, 16, v125
	v_and_b32_e32 v63, 0xffff0000, v125
	v_lshlrev_b32_e32 v160, 16, v140
	v_and_b32_e32 v161, 0xffff0000, v140
	v_lshlrev_b32_e32 v162, 16, v141
	v_and_b32_e32 v163, 0xffff0000, v141
	v_pk_add_f32 v[64:65], v[64:65], v[160:161]
	v_pk_add_f32 v[62:63], v[62:63], v[162:163]
	v_lshlrev_b32_e32 v70, 16, v126
	v_and_b32_e32 v71, 0xffff0000, v126
	v_lshlrev_b32_e32 v56, 16, v127
	v_and_b32_e32 v57, 0xffff0000, v127
	v_lshlrev_b32_e32 v160, 16, v142
	v_and_b32_e32 v161, 0xffff0000, v142
	v_lshlrev_b32_e32 v162, 16, v143
	v_and_b32_e32 v163, 0xffff0000, v143
	v_pk_add_f32 v[70:71], v[70:71], v[160:161]
	v_pk_add_f32 v[56:57], v[56:57], v[162:163]
	v_lshlrev_b32_e32 v68, 16, v128
	v_and_b32_e32 v69, 0xffff0000, v128
	v_lshlrev_b32_e32 v66, 16, v129
	v_and_b32_e32 v67, 0xffff0000, v129
	v_lshlrev_b32_e32 v160, 16, v144
	v_and_b32_e32 v161, 0xffff0000, v144
	v_lshlrev_b32_e32 v162, 16, v145
	v_and_b32_e32 v163, 0xffff0000, v145
	v_pk_add_f32 v[68:69], v[68:69], v[160:161]
	v_pk_add_f32 v[66:67], v[66:67], v[162:163]
	v_lshlrev_b32_e32 v74, 16, v130
	v_and_b32_e32 v75, 0xffff0000, v130
	v_lshlrev_b32_e32 v72, 16, v131
	v_and_b32_e32 v73, 0xffff0000, v131
	v_lshlrev_b32_e32 v160, 16, v146
	v_and_b32_e32 v161, 0xffff0000, v146
	v_lshlrev_b32_e32 v162, 16, v147
	v_and_b32_e32 v163, 0xffff0000, v147
	v_pk_add_f32 v[74:75], v[74:75], v[160:161]
	v_pk_add_f32 v[72:73], v[72:73], v[162:163]
	v_lshlrev_b32_e32 v78, 16, v132
	v_and_b32_e32 v79, 0xffff0000, v132
	v_lshlrev_b32_e32 v76, 16, v133
	v_and_b32_e32 v77, 0xffff0000, v133
	v_lshlrev_b32_e32 v160, 16, v148
	v_and_b32_e32 v161, 0xffff0000, v148
	v_lshlrev_b32_e32 v162, 16, v149
	v_and_b32_e32 v163, 0xffff0000, v149
	v_pk_add_f32 v[78:79], v[78:79], v[160:161]
	v_pk_add_f32 v[76:77], v[76:77], v[162:163]
	v_lshlrev_b32_e32 v84, 16, v134
	v_and_b32_e32 v85, 0xffff0000, v134
	v_lshlrev_b32_e32 v82, 16, v135
	v_and_b32_e32 v83, 0xffff0000, v135
	v_lshlrev_b32_e32 v160, 16, v150
	v_and_b32_e32 v161, 0xffff0000, v150
	v_lshlrev_b32_e32 v162, 16, v151
	v_and_b32_e32 v163, 0xffff0000, v151
	v_pk_add_f32 v[84:85], v[84:85], v[160:161]
	v_pk_add_f32 v[82:83], v[82:83], v[162:163]
	s_branch .LBB0_904
.Lnorm_noy2:
	v_lshlrev_b32_e32 v54, 16, v120
	v_and_b32_e32 v55, 0xffff0000, v120
	v_lshlrev_b32_e32 v52, 16, v121
	v_and_b32_e32 v53, 0xffff0000, v121
	v_lshlrev_b32_e32 v60, 16, v122
	v_and_b32_e32 v61, 0xffff0000, v122
	v_lshlrev_b32_e32 v58, 16, v123
	v_and_b32_e32 v59, 0xffff0000, v123
	v_lshlrev_b32_e32 v64, 16, v124
	v_and_b32_e32 v65, 0xffff0000, v124
	v_lshlrev_b32_e32 v62, 16, v125
	v_and_b32_e32 v63, 0xffff0000, v125
	v_lshlrev_b32_e32 v70, 16, v126
	v_and_b32_e32 v71, 0xffff0000, v126
	v_lshlrev_b32_e32 v56, 16, v127
	v_and_b32_e32 v57, 0xffff0000, v127
	v_lshlrev_b32_e32 v68, 16, v128
	v_and_b32_e32 v69, 0xffff0000, v128
	v_lshlrev_b32_e32 v66, 16, v129
	v_and_b32_e32 v67, 0xffff0000, v129
	v_lshlrev_b32_e32 v74, 16, v130
	v_and_b32_e32 v75, 0xffff0000, v130
	v_lshlrev_b32_e32 v72, 16, v131
	v_and_b32_e32 v73, 0xffff0000, v131
	v_lshlrev_b32_e32 v78, 16, v132
	v_and_b32_e32 v79, 0xffff0000, v132
	v_lshlrev_b32_e32 v76, 16, v133
	v_and_b32_e32 v77, 0xffff0000, v133
	v_lshlrev_b32_e32 v84, 16, v134
	v_and_b32_e32 v85, 0xffff0000, v134
	v_lshlrev_b32_e32 v82, 16, v135
	v_and_b32_e32 v83, 0xffff0000, v135
